# speedup vs baseline: 1.0063x; 1.0000x over previous
.LBB0_435:
	s_and_b64 vcc, exec, s[6:7]
	s_cbranch_vccz .LBB0_456
	s_nop 0
	v_mov_b32_e32 v16, v208
	s_movk_i32 s0, 0xffe0
	v_and_b32_e32 v0, 0x3fffffc0, v16
	v_lshl_add_u32 v182, v0, 2, s71
	v_ashrrev_i32_e32 v0, 1, v16
	v_bfi_b32 v0, s0, v0, v16
	v_ashrrev_i32_e32 v1, 31, v0
	v_lshlrev_b64 v[0:1], 8, v[0:1]
	v_lshrrev_b32_e32 v2, 1, v16
	v_lshl_add_u64 v[0:1], s[88:89], 0, v[0:1]
	v_and_b32_e32 v176, 16, v2
	v_mov_b32_e32 v177, v175
	v_lshl_add_u64 v[0:1], v[0:1], 0, v[176:177]
	global_load_dwordx4 v[126:129], v[0:1], off
	global_load_dwordx4 v[122:125], v[0:1], off offset:32
	global_load_dwordx4 v[118:121], v[0:1], off offset:64
	global_load_dwordx4 v[114:117], v[0:1], off offset:96
	global_load_dwordx4 v[110:113], v[0:1], off offset:128
	global_load_dwordx4 v[106:109], v[0:1], off offset:160
	global_load_dwordx4 v[102:105], v[0:1], off offset:192
	global_load_dwordx4 v[98:101], v[0:1], off offset:224
	v_ashrrev_i32_e32 v0, 4, v16
	v_and_b32_e32 v3, 0xfffff0, v0
	v_lshlrev_b32_e32 v187, 1, v0
	v_lshlrev_b32_e32 v1, 3, v16
	v_and_or_b32 v3, v187, 8, v3
	v_and_b32_e32 v2, 0x78, v1
	v_lshrrev_b32_e32 v4, 1, v0
	v_lshrrev_b32_e32 v3, 1, v3
	v_bfe_u32 v1, v1, 5, 2
	v_and_b32_e32 v5, 3, v0
	v_or_b32_e32 v3, v3, v1
	v_and_or_b32 v4, v4, 4, v5
	v_lshlrev_b32_e32 v194, 1, v2
	v_lshlrev_b32_e32 v3, 9, v3
	v_lshlrev_b32_e32 v4, 6, v4
	v_and_b32_e32 v2, 48, v194
	v_add_u32_e32 v18, 32, v0
	v_or3_b32 v17, v3, v4, v2
	v_and_b32_e32 v3, 0xfffff0, v18
	v_lshlrev_b32_e32 v5, 1, v18
	v_and_or_b32 v3, v5, 8, v3
	v_lshrrev_b32_e32 v3, 1, v3
	v_or_b32_e32 v1, v3, v1
	v_and_b32_e32 v183, 63, v16
	v_lshlrev_b32_e32 v1, 9, v1
	v_lshlrev_b32_e32 v20, 4, v16
	v_or3_b32 v19, v1, v4, v2
	v_lshlrev_b32_e32 v1, 3, v183
	v_and_b32_e32 v2, 0xc0, v20
	v_lshlrev_b32_e32 v3, 1, v16
	v_and_or_b32 v2, v1, 24, v2
	v_and_b32_e32 v3, 32, v3
	v_and_b32_e32 v1, 0x100, v1
	s_cmp_lg_u32 0, -1
	v_or3_b32 v177, v2, v3, v1
	s_cselect_b32 s0, 0, 0
	v_add_u32_e32 v184, s0, v177
	s_and_b64 s[0:1], s[94:95], exec
	s_cselect_b32 s4, 0x80, s86
	v_lshlrev_b32_e32 v21, 8, v0
	v_mul_lo_u32 v0, v187, s4
	s_cselect_b32 s1, s47, s41
	s_cselect_b32 s0, s46, s40
	v_or_b32_e32 v174, v0, v194
	s_waitcnt lgkmcnt(0)
	s_barrier
	global_load_dwordx4 v[0:3], v174, s[0:1]
	v_or_b32_e32 v178, v194, v21
	s_cselect_b32 s7, s51, s55
	s_cselect_b32 s6, s50, s54
	v_mov_b32_e32 v179, v175
	v_lshl_add_u64 v[32:33], s[6:7], 0, v[178:179]
	v_lshl_add_u64 v[4:5], s[0:1], 0, v[174:175]
	s_lshl_b32 s56, s4, 6
	v_add_co_u32_e32 v12, vcc, s73, v32
	v_lshl_add_u64 v[4:5], v[4:5], 0, s[56:57]
	s_nop 0
	v_addc_co_u32_e32 v13, vcc, 0, v33, vcc
	global_load_dwordx4 v[4:7], v[4:5], off
	v_add_u32_e32 v197, 0, v17
	global_load_dwordx4 v[8:11], v178, s[6:7]
	v_and_b32_e32 v34, 31, v16
	global_load_dwordx4 v[12:15], v[12:13], off
	v_lshl_add_u64 v[244:245], s[0:1], 0, v[174:175]
	v_mov_b32_e32 v246, s4
	v_lshlrev_b32_e32 v246, 7, v246
	v_mov_b32_e32 v247, 0
	v_lshl_add_u64 v[244:245], v[244:245], 0, v[246:247]
	global_load_dwordx4 v[228:231], v[244:245], off
	v_lshl_add_u64 v[246:247], v[244:245], 0, s[56:57]
	global_load_dwordx4 v[232:235], v[246:247], off
	v_add_co_u32_e32 v248, vcc, 0x4000, v32
	s_nop 0
	v_addc_co_u32_e32 v249, vcc, 0, v33, vcc
	global_load_dwordx4 v[236:239], v[248:249], off
	v_add_co_u32_e32 v250, vcc, 0x6000, v32
	s_nop 0
	v_addc_co_u32_e32 v251, vcc, 0, v33, vcc
	global_load_dwordx4 v[240:243], v[250:251], off
	s_waitcnt vmcnt(0)
	v_lshlrev_b32_e32 v35, 8, v34
	v_and_b32_e32 v44, 0x70, v20
	v_add_u32_e32 v198, 0, v19
	v_or_b32_e32 v36, 32, v176
	v_bitop3_b32 v36, v36, v35, v44 bitop3:0xde
	v_add_u32_e32 v189, 0, v36
	s_mov_b32 s7, s57
	v_lshl_add_u32 v185, v34, 2, v182
	s_waitcnt vmcnt(3)
	ds_write_b128 v197, v[0:3]
	v_and_b32_e32 v0, 0x70, v16
	v_bitop3_b32 v1, v194, v21, v0 bitop3:0xde
	v_add_u32_e32 v199, 0, v1
	v_lshlrev_b32_e32 v1, 8, v18
	v_bitop3_b32 v0, v194, v1, v0 bitop3:0xde
	v_add_u32_e32 v200, 0, v0
	v_bitop3_b32 v0, v176, v35, v44 bitop3:0xde
	v_add_u32_e32 v188, 0, v0
	s_waitcnt vmcnt(2)
	ds_write_b128 v198, v[4:7]
	s_waitcnt vmcnt(1)
	ds_write_b128 v199, v[8:11] offset:32768
	s_waitcnt vmcnt(0)
	ds_write_b128 v200, v[12:15] offset:32768
	s_waitcnt lgkmcnt(0)
	s_barrier
	ds_read_b128 v[0:3], v188 offset:32768
	ds_read_b128 v[4:7], v188 offset:40960
	s_waitcnt lgkmcnt(1)
	v_mfma_f32_32x32x16_bf16 v[16:31], v[0:3], v[126:129], 0
	ds_read_b128 v[36:39], v189 offset:32768
	ds_read_b128 v[40:43], v189 offset:40960
	s_waitcnt lgkmcnt(2)
	v_mfma_f32_32x32x16_bf16 v[0:15], v[4:7], v[126:129], 0
	s_waitcnt lgkmcnt(1)
	v_mfma_f32_32x32x16_bf16 v[16:31], v[36:39], v[122:125], v[16:31]
	v_or_b32_e32 v36, 64, v176
	v_bitop3_b32 v36, v36, v35, v44 bitop3:0xde
	v_add_u32_e32 v190, 0, v36
	s_waitcnt lgkmcnt(0)
	v_mfma_f32_32x32x16_bf16 v[0:15], v[40:43], v[122:125], v[0:15]
	ds_read_b128 v[36:39], v190 offset:32768
	ds_read_b128 v[40:43], v190 offset:40960
	s_waitcnt lgkmcnt(1)
	v_mfma_f32_32x32x16_bf16 v[16:31], v[36:39], v[118:121], v[16:31]
	v_or_b32_e32 v36, 0x60, v176
	v_bitop3_b32 v36, v36, v35, v44 bitop3:0xde
	v_add_u32_e32 v191, 0, v36
	s_waitcnt lgkmcnt(0)
	v_mfma_f32_32x32x16_bf16 v[0:15], v[40:43], v[118:121], v[0:15]
	ds_read_b128 v[36:39], v191 offset:32768
	ds_read_b128 v[40:43], v191 offset:40960
	s_waitcnt lgkmcnt(1)
	v_mfma_f32_32x32x16_bf16 v[16:31], v[36:39], v[114:117], v[16:31]
	v_or_b32_e32 v36, 0x80, v176
	v_bitop3_b32 v36, v36, v35, v44 bitop3:0xde
	v_add_u32_e32 v192, 0, v36
	s_waitcnt lgkmcnt(0)
	v_mfma_f32_32x32x16_bf16 v[0:15], v[40:43], v[114:117], v[0:15]
	ds_read_b128 v[36:39], v192 offset:32768
	ds_read_b128 v[40:43], v192 offset:40960
	s_waitcnt lgkmcnt(1)
	v_mfma_f32_32x32x16_bf16 v[16:31], v[36:39], v[110:113], v[16:31]
	v_or_b32_e32 v36, 0xa0, v176
	v_bitop3_b32 v36, v36, v35, v44 bitop3:0xde
	v_add_u32_e32 v193, 0, v36
	s_waitcnt lgkmcnt(0)
	v_mfma_f32_32x32x16_bf16 v[0:15], v[40:43], v[110:113], v[0:15]
	ds_read_b128 v[36:39], v193 offset:32768
	ds_read_b128 v[40:43], v193 offset:40960
	s_waitcnt lgkmcnt(1)
	v_mfma_f32_32x32x16_bf16 v[16:31], v[36:39], v[106:109], v[16:31]
	v_or_b32_e32 v36, 0xc0, v176
	v_bitop3_b32 v36, v36, v35, v44 bitop3:0xde
	v_add_u32_e32 v195, 0, v36
	s_waitcnt lgkmcnt(0)
	v_mfma_f32_32x32x16_bf16 v[0:15], v[40:43], v[106:109], v[0:15]
	ds_read_b128 v[36:39], v195 offset:32768
	ds_read_b128 v[40:43], v195 offset:40960
	s_waitcnt lgkmcnt(1)
	v_mfma_f32_32x32x16_bf16 v[16:31], v[36:39], v[102:105], v[16:31]
	v_or_b32_e32 v36, 0xe0, v176
	v_bitop3_b32 v35, v36, v35, v44 bitop3:0xde
	v_add_u32_e32 v196, 0, v35
	s_waitcnt lgkmcnt(0)
	v_mfma_f32_32x32x16_bf16 v[0:15], v[40:43], v[102:105], v[0:15]
	ds_read_b128 v[36:39], v196 offset:32768
	ds_read_b128 v[40:43], v196 offset:40960
	s_waitcnt lgkmcnt(1)
	v_mfma_f32_32x32x16_bf16 v[16:31], v[36:39], v[98:101], v[16:31]
	v_mov_b32_e32 v37, s59
	s_waitcnt lgkmcnt(0)
	v_mfma_f32_32x32x16_bf16 v[0:15], v[40:43], v[98:101], v[0:15]
	s_nop 8
	v_max_f32_e32 v35, v17, v17
	v_max_f32_e32 v36, v16, v16
	v_max_f32_e32 v35, v36, v35
	v_max3_f32 v35, v35, v18, v19
	v_max3_f32 v35, v35, v20, v21
	v_max3_f32 v35, v35, v22, v23
	v_max3_f32 v35, v35, v24, v25
	v_max3_f32 v35, v35, v26, v27
	v_max3_f32 v35, v35, v28, v29
	v_max3_f32 v35, v35, v30, v31
	v_max3_f32 v35, v35, v0, v1
	v_max3_f32 v35, v35, v2, v3
	v_max3_f32 v35, v35, v4, v5
	v_max3_f32 v35, v35, v6, v7
	v_max3_f32 v35, v35, v8, v9
	v_max3_f32 v35, v35, v10, v11
	v_max3_f32 v35, v35, v12, v13
	v_max3_f32 v35, v35, v14, v15
	v_mov_b32_e32 v36, v35
	s_nop 1
	v_permlane32_swap_b32_e32 v35, v36
	v_max_f32_e32 v36, v36, v36
	v_max_f32_e32 v35, v35, v35
	v_max_f32_e32 v35, v35, v36
	v_subrev_f32_e32 v36, s59, v35
	v_cmp_ge_f32_e32 vcc, s80, v36
	v_max_f32_e64 v36, s59, s59
	v_max_f32_e32 v35, v36, v35
	v_sub_f32_e32 v36, s59, v35
	v_mul_f32_e32 v36, 0x3e0293ee, v36
	v_exp_f32_e32 v36, v36
	s_cmp_eq_u64 vcc, exec
	s_cselect_b64 vcc, -1, 0
	s_lshl_b32 s6, s4, 7
	v_cndmask_b32_e32 v170, v35, v37, vcc
	s_add_u32 s8, s0, s6
	v_cndmask_b32_e64 v201, v36, 1.0, vcc
	v_mul_f32_e32 v36, 0xbe0293ee, v170
	s_addc_u32 s9, s1, 0
	s_movk_i32 s4, 0x4000
	s_lshl_b64 s[6:7], s[6:7], 1
	v_pk_fma_f32 v[152:153], v[8:9], s[74:75], v[36:37] op_sel_hi:[1,0,0]
	v_add_co_u32_e32 v8, vcc, s4, v32
	s_add_u32 s0, s0, s6
	v_fmamk_f32 v16, v16, 0x3e0293ee, v36
	v_fmamk_f32 v17, v17, 0x3e0293ee, v36
	v_addc_co_u32_e32 v9, vcc, 0, v33, vcc
	s_movk_i32 s4, 0x6000
	s_addc_u32 s1, s1, s7
	v_pk_fma_f32 v[148:149], v[12:13], s[74:75], v[36:37] op_sel_hi:[1,0,0]
	v_exp_f32_e32 v206, v16
	v_exp_f32_e32 v222, v17
	v_add_co_u32_e32 v12, vcc, s4, v32
	v_lshl_add_u64 v[16:17], s[0:1], 0, v[174:175]
	v_pk_fma_f32 v[158:159], v[2:3], s[74:75], v[36:37] op_sel_hi:[1,0,0]
	v_pk_fma_f32 v[160:161], v[0:1], s[74:75], v[36:37] op_sel_hi:[1,0,0]
	global_load_dwordx4 v[130:133], v174, s[0:1]
	v_addc_co_u32_e32 v13, vcc, 0, v33, vcc
	v_lshl_add_u64 v[16:17], v[16:17], 0, s[56:57]
	s_mov_b32 s0, 0x8000
	global_load_dwordx4 v[134:137], v[16:17], off
	v_add_co_u32_e32 v16, vcc, s0, v32
	s_mov_b32 s0, 0xa000
	s_nop 0
	v_addc_co_u32_e32 v17, vcc, 0, v33, vcc
	v_pk_fma_f32 v[156:157], v[4:5], s[74:75], v[36:37] op_sel_hi:[1,0,0]
	v_lshl_add_u64 v[4:5], s[8:9], 0, v[174:175]
	global_load_dwordx4 v[138:141], v[16:17], off
	v_add_co_u32_e32 v16, vcc, s0, v32
	v_lshl_add_u64 v[4:5], v[4:5], 0, s[56:57]
	s_nop 0
	v_addc_co_u32_e32 v17, vcc, 0, v33, vcc
	v_pk_fma_f32 v[154:155], v[6:7], s[74:75], v[36:37] op_sel_hi:[1,0,0]
	v_pk_fma_f32 v[150:151], v[10:11], s[74:75], v[36:37] op_sel_hi:[1,0,0]
	global_load_dwordx4 v[142:145], v[16:17], off
	v_pk_fma_f32 v[146:147], v[14:15], s[74:75], v[36:37] op_sel_hi:[1,0,0]
	v_mov_b32_e32 v35, v36
	v_fmamk_f32 v18, v18, 0x3e0293ee, v36
	v_fmamk_f32 v19, v19, 0x3e0293ee, v36
	v_fmamk_f32 v20, v20, 0x3e0293ee, v36
	v_fmamk_f32 v21, v21, 0x3e0293ee, v36
	v_fmamk_f32 v22, v22, 0x3e0293ee, v36
	v_fmamk_f32 v23, v23, 0x3e0293ee, v36
	v_fmamk_f32 v24, v24, 0x3e0293ee, v36
	v_fmamk_f32 v25, v25, 0x3e0293ee, v36
	v_fmamk_f32 v26, v26, 0x3e0293ee, v36
	v_fmamk_f32 v27, v27, 0x3e0293ee, v36
	v_fmamk_f32 v28, v28, 0x3e0293ee, v36
	v_fmamk_f32 v29, v29, 0x3e0293ee, v36
	v_fmamk_f32 v30, v30, 0x3e0293ee, v36
	v_fmac_f32_e32 v35, 0x3e0293ee, v31
	v_exp_f32_e32 v163, v18
	v_exp_f32_e32 v207, v19
	v_exp_f32_e32 v164, v20
	v_exp_f32_e32 v205, v21
	v_exp_f32_e32 v165, v22
	v_exp_f32_e32 v204, v23
	v_exp_f32_e32 v166, v24
	v_exp_f32_e32 v203, v25
	v_exp_f32_e32 v167, v26
	v_exp_f32_e32 v173, v27
	v_exp_f32_e32 v168, v28
	v_exp_f32_e32 v172, v29
	v_exp_f32_e32 v169, v30
	v_exp_f32_e32 v171, v35
	s_waitcnt vmcnt(4)
	ds_write_b128 v197, v[228:231] offset:16384
	ds_write_b128 v198, v[232:235] offset:16384
	ds_write_b128 v199, v[236:239] offset:49152
	ds_write_b128 v200, v[240:243] offset:49152
	v_mov_b32_e32 v15, 0
	s_cmp_lt_i32 s82, 3
	v_cmp_gt_u32_e64 s[6:7], 32, v183
	s_waitcnt lgkmcnt(0)
	s_barrier
	s_cbranch_scc1 .LBB0_448
	s_add_i32 s4, s82, -1
	s_cmp_lg_u32 0, -1
	s_cselect_b32 s0, 0, 0
	s_addk_i32 s0, 0x4000
	v_add_u32_e32 v202, s0, v177
	s_mov_b64 s[0:1], 0xe000
	v_mov_b32_e32 v16, 0
	v_lshl_add_u64 v[180:181], v[178:179], 0, s[0:1]
	s_mov_b64 s[0:1], 3
	v_mov_b32_e32 v186, s33
	v_mov_b32_e32 v17, v16
	v_mov_b32_e32 v18, v16
	v_mov_b32_e32 v19, v16
	v_mov_b32_e32 v20, v16
	v_mov_b32_e32 v21, v16
	v_mov_b32_e32 v22, v16
	v_mov_b32_e32 v23, v16
	v_mov_b32_e32 v24, v16
	v_mov_b32_e32 v25, v16
	v_mov_b32_e32 v26, v16
	v_mov_b32_e32 v27, v16
	v_mov_b32_e32 v28, v16
	v_mov_b32_e32 v29, v16
	v_mov_b32_e32 v30, v16
	v_mov_b32_e32 v31, v16
	v_mov_b32_e32 v32, v16
	v_mov_b32_e32 v33, v16
	v_mov_b32_e32 v34, v16
	v_mov_b32_e32 v35, v16
	v_mov_b32_e32 v36, v16
	v_mov_b32_e32 v37, v16
	v_mov_b32_e32 v38, v16
	v_mov_b32_e32 v39, v16
	v_mov_b32_e32 v40, v16
	v_mov_b32_e32 v41, v16
	v_mov_b32_e32 v42, v16
	v_mov_b32_e32 v43, v16
	v_mov_b32_e32 v44, v16
	v_mov_b32_e32 v45, v16
	v_mov_b32_e32 v46, v16
	v_mov_b32_e32 v47, v16
	v_mov_b32_e32 v48, v16
	v_mov_b32_e32 v49, v16
	v_mov_b32_e32 v50, v16
	v_mov_b32_e32 v51, v16
	v_mov_b32_e32 v52, v16
	v_mov_b32_e32 v53, v16
	v_mov_b32_e32 v54, v16
	v_mov_b32_e32 v55, v16
	v_mov_b32_e32 v56, v16
	v_mov_b32_e32 v57, v16
	v_mov_b32_e32 v58, v16
	v_mov_b32_e32 v59, v16
	v_mov_b32_e32 v60, v16
	v_mov_b32_e32 v61, v16
	v_mov_b32_e32 v62, v16
	v_mov_b32_e32 v63, v16
	v_mov_b32_e32 v0, v16
	v_mov_b32_e32 v1, v16
	v_mov_b32_e32 v2, v16
	v_mov_b32_e32 v3, v16
	v_mov_b32_e32 v4, v16
	v_mov_b32_e32 v5, v16
	v_mov_b32_e32 v6, v16
	v_mov_b32_e32 v7, v16
	v_mov_b32_e32 v8, v16
	v_mov_b32_e32 v9, v16
	v_mov_b32_e32 v10, v16
	v_mov_b32_e32 v11, v16
	v_mov_b32_e32 v12, v16
	v_mov_b32_e32 v13, v16
	v_mov_b32_e32 v14, v16
	v_mov_b32_e32 v15, v16
